# layer-1 w_in / w_out conversion moved into the workgroups that idle in the last round of layer 0's up-projection GEMM
# speedup vs baseline: 1.0015x; 1.0004x over previous
.LBB0_400:
	s_andn2_b64 vcc, exec, s[0:1]
	s_cbranch_vccnz .LBB0_558
	s_cmp_lg_u32 s63, 0
	s_cselect_b64 s[2:3], -1, 0
	s_and_b64 vcc, exec, s[2:3]
	s_cbranch_vccnz .LBB0_437
	s_mov_b32 s30, 0
	v_readlane_b32 s0, v253, 0
	v_readlane_b32 s1, v254, 21
	s_mov_b32 s28, s54
	s_movk_i32 s29, 0x1990
	s_and_b32 s6, s1, 0xffff
	s_mul_i32 s27, s6, 0x910
	s_branch .Lec_common
.Lec_entry:
	s_sub_u32 s0, s1, 0x96
	s_movk_i32 s28, 0x6a
	s_movk_i32 s29, 0x910
	s_mov_b32 s6, 1
	s_mov_b32 s27, 0
.Lec_common:
	s_mov_b64 s[8:9], s[36:37]
	s_waitcnt vmcnt(0)
	v_mov_b32_e32 v1, v224
	v_ashrrev_i32_e32 v0, 6, v1
	v_lshl_add_u32 v4, s0, 3, v0
	v_add_u32_e32 v4, s27, v4
	s_mov_b32 s0, s28
	v_cmp_gt_i32_e32 vcc, s29, v4
	s_and_saveexec_b64 s[10:11], vcc
	s_cbranch_execz .LBB0_421
	s_load_dwordx2 s[4:5], s[8:9], 0x48
	s_load_dwordx4 s[20:23], s[8:9], 0x78
	s_lshl_b32 s7, s0, 3
	s_mul_i32 s1, s6, 0xe08000
	v_and_b32_e32 v3, 7, v1
	s_waitcnt lgkmcnt(0)
	s_add_u32 s14, s4, s1
	s_addc_u32 s15, s5, 0
	s_lshl_b32 s1, s6, 22
	s_load_dwordx2 s[4:5], s[8:9], 0x98
	s_add_u32 s18, s20, s1
	s_addc_u32 s19, s21, 0
	s_mul_i32 s1, s6, 0x1600000
	s_add_u32 s20, s22, s1
	s_addc_u32 s21, s23, 0
	s_mul_i32 s1, s6, 0xb00000
	s_waitcnt lgkmcnt(0)
	s_add_u32 s34, s4, s1
	s_movk_i32 s1, 0x2100
	v_mul_lo_u32 v0, v0, s1
	v_add_u32_e32 v2, s24, v0
	v_bfe_u32 v6, v1, 3, 3
	v_lshlrev_b32_e32 v5, 2, v3
	v_lshl_add_u32 v7, v3, 4, v2
	v_lshlrev_b32_e32 v0, 3, v3
	v_mul_u32_u24_e32 v3, 0x420, v3
	v_lshlrev_b32_e32 v12, 2, v6
	v_add3_u32 v12, v2, v3, v12
	v_mov_b32_e32 v2, 0xfffd7e00
	v_lshl_add_u32 v13, v4, 5, v2
	v_mov_b32_e32 v2, 0xffffd7e0
	s_addc_u32 s35, s5, 0
	v_mul_u32_u24_e32 v8, 0x84, v6
	v_or_b32_e32 v9, 8, v6
	v_or_b32_e32 v10, 16, v6
	v_or_b32_e32 v11, 24, v6
	s_lshl_b32 s12, s0, 8
	v_lshl_add_u32 v14, v4, 1, v2
	s_lshl_b32 s13, s0, 4
	s_mov_b64 s[38:39], 0
	s_branch .LBB0_405
.LBB0_404:
	s_or_b64 exec, exec, s[4:5]
	v_add_u32_e32 v4, s7, v4
	s_nop 0
	v_cmp_le_i32_e32 vcc, s29, v4
	v_add_u32_e32 v13, s12, v13
	s_or_b64 s[38:39], vcc, s[38:39]
	v_add_u32_e32 v14, s13, v14
	s_andn2_b64 exec, exec, s[38:39]
	s_cbranch_execz .LBB0_421

.LBB0_421:
	s_or_b64 exec, exec, s[10:11]
	s_cmp_eq_u32 s30, 1
	s_cbranch_scc1 .Lec_return
	s_load_dwordx4 s[12:15], s[8:9], 0x10
	s_load_dwordx2 s[4:5], s[8:9], 0xa8
	s_lshl_b32 s20, s6, 23
	v_readlane_b32 s10, v253, 0
	s_nop 0
	v_lshl_add_u32 v0, s10, 9, v224
	v_lshlrev_b32_e32 v1, 5, v0
	v_lshlrev_b32_e32 v2, 4, v0
	s_waitcnt lgkmcnt(0)
	s_add_u32 s12, s12, s20
	s_addc_u32 s13, s13, 0
	s_add_u32 s14, s14, s20
	s_addc_u32 s15, s15, 0
	s_add_u32 s18, s12, 0x400000
	s_addc_u32 s19, s13, 0
	s_add_u32 s38, s14, 0x400000
	s_addc_u32 s39, s15, 0
	global_load_dwordx4 v[8:11], v1, s[12:13] nt
	global_load_dwordx4 v[12:15], v1, s[12:13] offset:16 nt
	global_load_dwordx4 v[16:19], v1, s[18:19] nt
	global_load_dwordx4 v[20:23], v1, s[18:19] offset:16 nt
	global_load_dwordx4 v[24:27], v1, s[14:15] nt
	global_load_dwordx4 v[28:31], v1, s[14:15] offset:16 nt
	global_load_dwordx4 v[32:35], v1, s[38:39] nt
	global_load_dwordx4 v[36:39], v1, s[38:39] offset:16 nt
	s_add_u32 s12, s4, 0xf400000
	s_addc_u32 s13, s5, 0
	s_add_u32 s18, s12, 0x200000
	s_addc_u32 s19, s13, 0
	s_add_u32 s14, s4, 0xf800000
	s_addc_u32 s15, s5, 0
	s_add_u32 s38, s14, 0x200000
	s_addc_u32 s39, s15, 0
	s_waitcnt vmcnt(6)
	v_cvt_pk_bf16_f32 v40, v8, v9
	v_cvt_pk_bf16_f32 v41, v10, v11
	v_cvt_pk_bf16_f32 v42, v12, v13
	v_cvt_pk_bf16_f32 v43, v14, v15
	global_store_dwordx4 v2, v[40:43], s[12:13]
	s_waitcnt vmcnt(5)
	v_cvt_pk_bf16_f32 v44, v16, v17
	v_cvt_pk_bf16_f32 v45, v18, v19
	v_cvt_pk_bf16_f32 v46, v20, v21
	v_cvt_pk_bf16_f32 v47, v22, v23
	global_store_dwordx4 v2, v[44:47], s[18:19]
	s_waitcnt vmcnt(4)
	v_cvt_pk_bf16_f32 v48, v24, v25
	v_cvt_pk_bf16_f32 v49, v26, v27
	v_cvt_pk_bf16_f32 v50, v28, v29
	v_cvt_pk_bf16_f32 v51, v30, v31
	global_store_dwordx4 v2, v[48:51], s[14:15]
	s_waitcnt vmcnt(3)
	v_cvt_pk_bf16_f32 v52, v32, v33
	v_cvt_pk_bf16_f32 v53, v34, v35
	v_cvt_pk_bf16_f32 v54, v36, v37
	v_cvt_pk_bf16_f32 v55, v38, v39
	global_store_dwordx4 v2, v[52:55], s[38:39]

.LBB0_654:
	v_readlane_b32 s0, v254, 23
	v_readlane_b32 s1, v253, 0
	s_cmp_eq_u32 s0, 7
	s_cbranch_scc0 .Lec_skip
	s_cmp_lt_u32 s1, 0x96
	s_cbranch_scc1 .Lec_skip
	s_mov_b32 s30, 1
	s_branch .Lec_entry
.Lec_return:
	s_mov_b32 s30, 0
